# phase E item loop: trailing stores of an item no longer drained (vmcnt(0)) at the loop top; prefetched index is complete by then
# baseline (speedup 1.0000x reference)
; DI void nsa_item(int wv0, PP p, int item, unsigned char* smem) {
;   const int tid = my_tid(wv0), lane = tid & 63, wv = wv0 & 3, hp = wv0 >> 2, l15 = lane & 15, lg = lane >> 4;
;   const int i = 127 - (item >> 3), bg = item & 7, b = bg >> 1, g = bg & 1;
;   u16* sK = (u16*)smem;
;   u16* sV = sK + 64 * 72;
;   float* sImp0 = (float*)(smem + 55296);
;   float* sImp = sImp0 + hp * (64 * 132);
;   u64* sUni = (u64*)(smem + 55296 + 2 * 64 * 132 * 4);
;   u64* sSel = sUni + 16;
;   const int t0 = i * 64, qloc = 16 * wv + l15, tq = t0 + qloc;
;   const unsigned tokq = (unsigned)(b * S_ + tq);
;   const float* NGb = (const float*)(p->ws + OFF_NG);
;   const unsigned ngoff = tokq * 24 + g * 12 + hp * 6;
;   float* ACCb = p->out;
;   const unsigned aoff = tokq * 512 + g * 256 + hp * 128 + 4 * lg;
;   const unsigned qoff = tokq * 512 + g * 256 + hp * 128 + lg * 8;
;   const int lrow = tid >> 3, lpart = tid & 7;
;   const unsigned koff = (lrow * 64 + lpart * 8) * 2, voffc = (lrow * 512 + lpart * 8) * 2, voffs = (lrow * S_ + lpart * 8) * 2;
;   for (int e = tid; e < 2 * 64 * 132; e += NT_) sImp0[e] = 0.f;
;   bf16x8 qf[2][2];
;   f32x4 O[2][4];
;   float m[2], l[2], ps[4][4];
;   u32x4 pk0, pv0;
;   auto nomask = [](int, int) { return true; };
; DI void phaseE(int wv0, PP p, unsigned char* smem, int cidx) {
;   __shared__ int s_item;
;   int* ctr = (int*)(p->ws + OFF_CTR) + cidx;
;   for (;;) {
;     __syncthreads();
;     if (my_tid(wv0) == 0) s_item = atomicAdd(ctr, 1);
;     __syncthreads();
;     const int item = s_item;
;     if (item >= 1024 + 2048 + (NXT - NXT_A)) break;
.LBB0_722:
	v_writelane_b32 v247, s48, 7
	s_mul_i32 s0, s89, 0x2100
	s_mul_i32 s1, s89, 0x1100
	v_writelane_b32 v247, s49, 8
	v_writelane_b32 v247, s94, 9
	v_and_b32_e32 v1, 0xffffffc0, v2
	v_readlane_b32 s4, v247, 5
	v_readlane_b32 s5, v247, 6
	s_load_dwordx2 s[2:3], s[4:5], 0xc8
	v_xor_b32_e32 v0, 16, v2
	v_add_u32_e32 v1, 64, v1
	v_cmp_lt_i32_e32 vcc, v0, v1
	s_mov_b32 s71, 0x20000
	s_waitcnt lgkmcnt(0)
	s_add_u32 s6, s2, 0x1fd0000
	s_addc_u32 s7, s3, 0
	v_writelane_b32 v247, s6, 10
	v_cndmask_b32_e32 v0, v2, v0, vcc
	v_lshlrev_b32_e32 v144, 2, v0
	v_writelane_b32 v247, s7, 11
	s_add_u32 s6, s4, 0xb0
	s_addc_u32 s7, s5, 0
	v_writelane_b32 v247, s6, 12
	v_xor_b32_e32 v0, 32, v2
	v_cmp_lt_i32_e32 vcc, v0, v1
	v_writelane_b32 v247, s7, 13
	s_add_u32 s6, s2, 0x1740000
	s_addc_u32 s7, s3, 0
	v_writelane_b32 v247, s6, 14
	v_cndmask_b32_e32 v0, v2, v0, vcc
	v_lshlrev_b32_e32 v145, 2, v0
	v_writelane_b32 v247, s7, 15
	s_add_u32 s6, s4, 0xa8
	s_addc_u32 s7, s5, 0
	v_writelane_b32 v247, s6, 16
	v_mov_b32_e32 v1, 0
	s_brev_b32 s70, -2
	v_writelane_b32 v247, s7, 17
	s_add_u32 s6, s2, 0xf40000
	s_addc_u32 s7, s3, 0
	v_writelane_b32 v247, s6, 18
	s_brev_b32 s83, -4
	v_mov_b32_e32 v146, 0x260
	v_writelane_b32 v247, s7, 19
	s_add_u32 s6, s4, 0x98
	s_addc_u32 s7, s5, 0
	v_writelane_b32 v247, s6, 20
	v_mov_b32_e32 v136, 0x3a83126f
	v_mov_b32_e32 v147, 0x34f
	v_writelane_b32 v247, s7, 21
	s_add_u32 s6, s2, 0xd40000
	s_addc_u32 s7, s3, 0
	v_writelane_b32 v247, s6, 22
	v_mov_b32_e32 v148, 0xf149f2ca
	v_mov_b32_e32 v149, 0x447a0000
	v_writelane_b32 v247, s7, 23
	s_add_u32 s6, s4, 0x90
	s_addc_u32 s7, s5, 0
	v_writelane_b32 v247, s6, 24
	v_mov_b32_e32 v150, 0x7149f2ca
	s_nop 0
	v_writelane_b32 v247, s7, 25
	s_add_u32 s6, s2, 0xb40000
	s_addc_u32 s7, s3, 0
	v_writelane_b32 v247, s6, 26
	s_nop 1
	v_writelane_b32 v247, s7, 27
	s_add_u32 s6, s4, 0x88
	s_addc_u32 s7, s5, 0
	v_writelane_b32 v247, s6, 28
	s_add_u32 s4, s4, 0x80
	s_addc_u32 s5, s5, 0
	v_writelane_b32 v247, s7, 29
	v_writelane_b32 v247, s4, 30
	s_nop 1
	v_writelane_b32 v247, s5, 31
	s_add_u32 s4, s2, 0xa40000
	s_addc_u32 s5, s3, 0
	v_writelane_b32 v247, s4, 32
	s_nop 1
	v_writelane_b32 v247, s5, 33
	s_add_u32 s4, s2, 0x1e3d4100
	v_writelane_b32 v247, s4, 34
	s_addc_u32 s4, s3, 0
	v_writelane_b32 v247, s4, 35
	s_add_u32 s4, s2, 0x1e414100
	s_addc_u32 s5, s3, 0
	v_writelane_b32 v247, s4, 36
	s_nop 1
	v_writelane_b32 v247, s5, 37
	s_add_u32 s4, s2, 0x2bd4100
	v_writelane_b32 v247, s4, 38
	s_addc_u32 s4, s3, 0
	v_writelane_b32 v247, s4, 39
	s_add_u32 s4, s2, 0x163d4100
	v_writelane_b32 v247, s4, 40
	s_addc_u32 s4, s3, 0
	v_writelane_b32 v247, s4, 41
	s_add_u32 s4, s2, 0x1a3d4100
	v_writelane_b32 v247, s4, 42
	s_addc_u32 s4, s3, 0
	v_writelane_b32 v247, s4, 43
	v_writelane_b32 v247, s1, 44
	s_add_i32 s1, s1, 32
	s_add_i32 s4, s0, 32
	v_writelane_b32 v247, s4, 45
	s_add_i32 s1, s1, 0x12800
	v_writelane_b32 v247, s1, 46
	s_lshl_b32 s5, s89, 4
	s_lshr_b32 s1, s82, 8
	v_writelane_b32 v247, s89, 47
	s_and_b32 s45, s5, 48
	v_writelane_b32 v247, s5, 48
	s_add_u32 s94, s2, 0x23d4100
	s_mul_i32 s5, s1, 6
	s_addc_u32 s95, s3, 0
	v_writelane_b32 v247, s5, 49
	s_lshl_b32 s5, s1, 7
	s_add_u32 s6, s2, 0x2ad4100
	v_writelane_b32 v247, s6, 51
	s_addc_u32 s6, s3, 0
	v_writelane_b32 v247, s6, 52
	s_add_u32 s6, s2, 0x2b54100
	v_writelane_b32 v247, s6, 53
	s_addc_u32 s6, s3, 0
	v_writelane_b32 v247, s6, 54
	s_add_u32 s6, s2, 0xf3d4100
	s_addc_u32 s7, s3, 0
	s_add_u32 s86, s2, 0x113d4100
	v_writelane_b32 v247, s6, 55
	s_addc_u32 s87, s3, 0
	s_mul_i32 s4, s1, 0x8400
	v_writelane_b32 v247, s7, 56
	s_add_u32 s6, s2, 0x1fd0040
	s_addc_u32 s7, s3, 0
	v_writelane_b32 v247, s6, 57
	s_mulk_i32 s1, 0x1080
	s_mov_b32 s89, 0
	v_writelane_b32 v247, s7, 58
	s_add_u32 s6, s2, 0x143d4100
	v_writelane_b32 v247, s6, 59
	s_addc_u32 s6, s3, 0
	v_writelane_b32 v247, s6, 60
	s_add_u32 s6, s2, 0x14bd4100
	v_writelane_b32 v247, s6, 61
	s_addc_u32 s6, s3, 0
	v_writelane_b32 v247, s6, 62
	s_add_u32 s6, s2, 0x153d4100
	v_writelane_b32 v247, s6, 63
	s_addc_u32 s6, s3, 0
	v_writelane_b32 v246, s6, 0
	s_add_u32 s6, s2, 0x15bd4100
	v_writelane_b32 v246, s6, 1
	s_addc_u32 s6, s3, 0
	s_add_u32 s78, s2, 0x183d4100
	v_writelane_b32 v246, s6, 2
	s_addc_u32 s79, s3, 0
	s_addk_i32 s0, 0x2000
	v_writelane_b32 v246, s0, 3
	s_add_i32 s0, s4, 32
	s_add_i32 s0, s0, 0xd800
	v_writelane_b32 v246, s0, 4
	s_bfe_u32 s0, s82, 0x20006
	s_lshl_b32 s2, s0, 8
	v_writelane_b32 v246, s5, 5
	s_add_i32 s2, s2, s5
	s_mulk_i32 s0, 0x2100
	v_writelane_b32 v246, s2, 6
	s_add_i32 s0, s0, s1
	v_writelane_b32 v246, s0, 7
	s_add_i32 s2, 32, 0x1e010
	v_writelane_b32 v246, s2, 8
	s_add_i32 s2, 32, 0x1e020
	v_writelane_b32 v246, s2, 9
	s_add_i32 s2, 32, 0x1e030
	v_writelane_b32 v246, s2, 10
	s_add_i32 s2, 32, 0x1e040
	v_writelane_b32 v246, s2, 11
	s_add_i32 s2, 32, 0x1e050
	v_writelane_b32 v246, s2, 12
	s_add_i32 s2, 32, 0x1e060
	v_writelane_b32 v246, s2, 13
	s_add_i32 s2, 32, 0x1e070
	s_movk_i32 s0, 0x7f
	s_mov_b32 s1, 0xf149f2ca
	s_mov_b32 s82, 0xefa18f08
	v_writelane_b32 v246, s2, 14
	v_writelane_b32 v246, s45, 15
	v_cmp_eq_u32_e32 vcc, 0, v137
	s_and_saveexec_b64 s[2:3], vcc
	s_cbranch_execz .Lmy_q_init_done
	v_mov_b32_e32 v253, 1
	v_readlane_b32 s6, v247, 10
	v_readlane_b32 s7, v247, 11
	s_nop 4
	global_atomic_add v252, v1, v253, s[6:7] sc0
	s_waitcnt vmcnt(0)

; DI void phaseE(int wv0, PP p, unsigned char* smem, int cidx) {
;     ...
;   for (;;) {
;     __syncthreads();
;     if (my_tid(wv0) == 0) s_item = atomicAdd(ctr, 1);
;     __syncthreads();
;     const int item = s_item;
;     if (item >= 1024 + 2048 + (NXT - NXT_A)) break;
.LBB0_726:
	v_mov_b32_e32 v0, v137
	s_barrier
	s_nop 0
	v_cmp_eq_u32_e32 vcc, 0, v0
	s_and_saveexec_b64 s[2:3], vcc
	s_cbranch_execz .LBB0_730
	ds_write_b32 v1, v252 offset:16
	v_mov_b32_e32 v253, 1
	v_readlane_b32 s6, v247, 10
	v_readlane_b32 s7, v247, 11
	s_nop 4
	global_atomic_add v252, v1, v253, s[6:7] sc0
